# baseline (speedup 1.0000x reference)
; #define MFMA16(a, b, c) __builtin_amdgcn_mfma_f32_16x16x32_bf16(a, b, c, 0, 0, 0)
; template <int DH, int MODE>
; __device__ void attn_item(const Params& p, int layer, int b, int blk, int head, char* smem) {
;     ...
;     if (!wskip) {
;     if (MODE == 0) {
; #pragma unroll
;       for (int m = 0; m < 2; ++m)
; #pragma unroll
;         for (int j = 0; j < 4; ++j) {
;           float al = alpha_s[wid * 32 + m * 16 + fq * 4 + j];
; #pragma unroll
;           for (int n = 0; n < NDT; ++n) o[m][n][j] *= al;
;         }
;     }
; #pragma unroll
;     for (int ks = 0; ks < 2; ++ks) {
;       bf16x8 af[2];
; #pragma unroll
;       for (int m = 0; m < 2; ++m)
;         af[m] = *reinterpret_cast<const bf16x8*>(Pb + ks * 8192 + (wid * 32 + m * 16 + fr) * 64 + fq * 16);
; #pragma unroll
;       for (int n = 0; n < NDT; ++n) {
;         bf16x8 bfr = *reinterpret_cast<const bf16x8*>(smem + ks * (DH * 64) + (n * 16 + fr) * 64 + fq * 16);
; #pragma unroll
;         for (int m = 0; m < 2; ++m) o[m][n] = MFMA16(af[m], bfr, o[m][n]);
;       }
;     }
.LBB0_188:
	s_or_b64 exec, exec, s[52:53]
	s_waitcnt lgkmcnt(0)
	s_barrier
	s_and_saveexec_b64 s[6:7], s[50:51]
	s_cbranch_execz .LBB0_163
	ds_read_b128 v[164:167], v99 offset:51200
	ds_read_b128 v[168:171], v98 offset:8192
	ds_read_b128 v[172:175], v99 offset:52224
	ds_read_b128 v[176:179], v100
	ds_read_b128 v[180:183], v98 offset:8256
	ds_read_b128 v[184:187], v100 offset:1024
	ds_read_b128 v[188:191], v100 offset:2048
	ds_read_b128 v[192:195], v100 offset:3072
	ds_read_b128 v[196:199], v99 offset:59392
	ds_read_b128 v[200:203], v99 offset:60416
	ds_read_b128 v[204:207], v100 offset:4096
	ds_read_b128 v[208:211], v100 offset:5120
	ds_read_b128 v[212:215], v100 offset:6144
	ds_read_b128 v[216:219], v100 offset:7168
	s_waitcnt lgkmcnt(12)
	v_pk_mul_f32 v[18:19], v[18:19], v[170:171]
	v_pk_mul_f32 v[16:17], v[16:17], v[168:169]
	v_pk_mul_f32 v[30:31], v[30:31], v[170:171]
	s_waitcnt lgkmcnt(9)
	v_pk_mul_f32 v[14:15], v[14:15], v[182:183]
	v_pk_mul_f32 v[12:13], v[12:13], v[180:181]
	v_pk_mul_f32 v[28:29], v[28:29], v[168:169]
	v_pk_mul_f32 v[10:11], v[10:11], v[182:183]
	v_pk_mul_f32 v[8:9], v[8:9], v[180:181]
	v_mfma_f32_16x16x32_bf16 v[16:19], v[164:167], v[176:179], v[16:19]
	v_mul_f32_e64 v26, v26, v170
	v_mul_f32_e64 v27, v27, v171
	v_pk_mul_f32 v[24:25], v[24:25], v[168:169]
	v_pk_mul_f32 v[22:23], v[22:23], v[170:171]
	v_mfma_f32_16x16x32_bf16 v[12:15], v[172:175], v[176:179], v[12:15]
	v_pk_mul_f32 v[20:21], v[20:21], v[168:169]
	v_pk_mul_f32 v[6:7], v[6:7], v[182:183]
	s_waitcnt lgkmcnt(8)
	v_mfma_f32_16x16x32_bf16 v[28:31], v[164:167], v[184:187], v[28:31]
	v_mul_f32_e64 v4, v4, v180
	v_mul_f32_e64 v5, v5, v181
	v_pk_mul_f32 v[2:3], v[2:3], v[182:183]
	v_pk_mul_f32 v[0:1], v[0:1], v[180:181]
	v_mfma_f32_16x16x32_bf16 v[8:11], v[172:175], v[184:187], v[8:11]
	s_waitcnt lgkmcnt(7)
	v_mfma_f32_16x16x32_bf16 v[24:27], v[164:167], v[188:191], v[24:27]
	s_waitcnt lgkmcnt(6)
	v_mfma_f32_16x16x32_bf16 v[20:23], v[164:167], v[192:195], v[20:23]
	v_mfma_f32_16x16x32_bf16 v[4:7], v[172:175], v[188:191], v[4:7]
	v_mfma_f32_16x16x32_bf16 v[0:3], v[172:175], v[192:195], v[0:3]
	s_waitcnt lgkmcnt(3)
	v_mfma_f32_16x16x32_bf16 v[16:19], v[196:199], v[204:207], v[16:19]
	v_mfma_f32_16x16x32_bf16 v[12:15], v[200:203], v[204:207], v[12:15]
	s_waitcnt lgkmcnt(2)
	v_mfma_f32_16x16x32_bf16 v[28:31], v[196:199], v[208:211], v[28:31]
	v_mfma_f32_16x16x32_bf16 v[8:11], v[200:203], v[208:211], v[8:11]
	s_waitcnt lgkmcnt(1)
	v_mfma_f32_16x16x32_bf16 v[24:27], v[196:199], v[212:215], v[24:27]
	v_mfma_f32_16x16x32_bf16 v[4:7], v[200:203], v[212:215], v[4:7]
	s_waitcnt lgkmcnt(0)
	v_mfma_f32_16x16x32_bf16 v[20:23], v[196:199], v[216:219], v[20:23]
	v_mfma_f32_16x16x32_bf16 v[0:3], v[200:203], v[216:219], v[0:3]
	s_branch .LBB0_163

; #define MFMA16(a, b, c) __builtin_amdgcn_mfma_f32_16x16x32_bf16(a, b, c, 0, 0, 0)
; template <int DH, int MODE>
; __device__ void attn_item(const Params& p, int layer, int b, int blk, int head, char* smem) {
;     ...
; #pragma unroll
;     for (int ks = 0; ks < 2; ++ks) {
;       bf16x8 af[2];
; #pragma unroll
;       for (int m = 0; m < 2; ++m)
;         af[m] = *reinterpret_cast<const bf16x8*>(Pb + ks * 8192 + (wid * 32 + m * 16 + fr) * 64 + fq * 16);
; #pragma unroll
;       for (int n = 0; n < NDT; ++n) {
;         bf16x8 bfr = *reinterpret_cast<const bf16x8*>(smem + ks * (DH * 64) + (n * 16 + fr) * 64 + fq * 16);
; #pragma unroll
;         for (int m = 0; m < 2; ++m) o[m][n] = MFMA16(af[m], bfr, o[m][n]);
;       }
;     }
.LBB0_214:
	s_or_b64 exec, exec, s[50:51]
	s_waitcnt lgkmcnt(0)
	s_barrier
	s_and_saveexec_b64 s[50:51], s[8:9]
	s_cbranch_execz .LBB0_216
	ds_read_b128 v[176:179], v172 offset:51200
	ds_read_b128 v[180:183], v172 offset:52224
	ds_read_b128 v[184:187], v128
	ds_read_b128 v[188:191], v128 offset:1024
	ds_read_b128 v[192:195], v128 offset:2048
	ds_read_b128 v[196:199], v128 offset:3072
	ds_read_b128 v[200:203], v128 offset:4096
	ds_read_b128 v[204:207], v128 offset:5120
	ds_read_b128 v[208:211], v128 offset:6144
	ds_read_b128 v[212:215], v128 offset:7168
	ds_read_b128 v[216:219], v172 offset:59392
	ds_read_b128 v[220:223], v172 offset:60416
	ds_read_b128 v[224:227], v128 offset:8192
	ds_read_b128 v[228:231], v128 offset:9216
	s_waitcnt lgkmcnt(11)
	v_mfma_f32_16x16x32_bf16 v[12:15], v[176:179], v[184:187], v[12:15]
	v_mfma_f32_16x16x32_bf16 v[16:19], v[180:183], v[184:187], v[16:19]
	s_waitcnt lgkmcnt(10)
	v_mfma_f32_16x16x32_bf16 v[48:51], v[176:179], v[188:191], v[48:51]
	v_mfma_f32_16x16x32_bf16 v[20:23], v[180:183], v[188:191], v[20:23]
	s_waitcnt lgkmcnt(9)
	v_mfma_f32_16x16x32_bf16 v[52:55], v[176:179], v[192:195], v[52:55]
	v_mfma_f32_16x16x32_bf16 v[24:27], v[180:183], v[192:195], v[24:27]
	s_waitcnt lgkmcnt(8)
	v_mfma_f32_16x16x32_bf16 v[56:59], v[176:179], v[196:199], v[56:59]
	v_mfma_f32_16x16x32_bf16 v[36:39], v[180:183], v[196:199], v[36:39]
	s_waitcnt lgkmcnt(7)
	v_mfma_f32_16x16x32_bf16 v[60:63], v[176:179], v[200:203], v[60:63]
	v_mfma_f32_16x16x32_bf16 v[28:31], v[180:183], v[200:203], v[28:31]
	s_waitcnt lgkmcnt(6)
	v_mfma_f32_16x16x32_bf16 v[64:67], v[176:179], v[204:207], v[64:67]
	v_mfma_f32_16x16x32_bf16 v[40:43], v[180:183], v[204:207], v[40:43]
	s_waitcnt lgkmcnt(5)
	v_mfma_f32_16x16x32_bf16 v[68:71], v[176:179], v[208:211], v[68:71]
	s_waitcnt lgkmcnt(4)
	v_mfma_f32_16x16x32_bf16 v[72:75], v[176:179], v[212:215], v[72:75]
	ds_read_b128 v[176:179], v128 offset:10240
	v_mfma_f32_16x16x32_bf16 v[44:47], v[180:183], v[208:211], v[44:47]
	v_mfma_f32_16x16x32_bf16 v[32:35], v[180:183], v[212:215], v[32:35]
	ds_read_b128 v[180:183], v128 offset:11264
	ds_read_b128 v[184:187], v128 offset:12288
	ds_read_b128 v[188:191], v128 offset:13312
	ds_read_b128 v[192:195], v128 offset:14336
	ds_read_b128 v[196:199], v128 offset:15360
	s_waitcnt lgkmcnt(7)
	v_mfma_f32_16x16x32_bf16 v[12:15], v[216:219], v[224:227], v[12:15]
	v_mfma_f32_16x16x32_bf16 v[16:19], v[220:223], v[224:227], v[16:19]
	s_waitcnt lgkmcnt(6)
	v_mfma_f32_16x16x32_bf16 v[48:51], v[216:219], v[228:231], v[48:51]
	v_mfma_f32_16x16x32_bf16 v[20:23], v[220:223], v[228:231], v[20:23]
	s_waitcnt lgkmcnt(5)
	v_mfma_f32_16x16x32_bf16 v[52:55], v[216:219], v[176:179], v[52:55]
	v_mfma_f32_16x16x32_bf16 v[24:27], v[220:223], v[176:179], v[24:27]
	s_waitcnt lgkmcnt(4)
	v_mfma_f32_16x16x32_bf16 v[56:59], v[216:219], v[180:183], v[56:59]
	v_mfma_f32_16x16x32_bf16 v[36:39], v[220:223], v[180:183], v[36:39]
	s_waitcnt lgkmcnt(3)
	v_mfma_f32_16x16x32_bf16 v[60:63], v[216:219], v[184:187], v[60:63]
	v_mfma_f32_16x16x32_bf16 v[28:31], v[220:223], v[184:187], v[28:31]
	s_waitcnt lgkmcnt(2)
	v_mfma_f32_16x16x32_bf16 v[64:67], v[216:219], v[188:191], v[64:67]
	v_mfma_f32_16x16x32_bf16 v[40:43], v[220:223], v[188:191], v[40:43]
	s_waitcnt lgkmcnt(1)
	v_mfma_f32_16x16x32_bf16 v[68:71], v[216:219], v[192:195], v[68:71]
	v_mfma_f32_16x16x32_bf16 v[44:47], v[220:223], v[192:195], v[44:47]
	s_waitcnt lgkmcnt(0)
	v_mfma_f32_16x16x32_bf16 v[72:75], v[216:219], v[196:199], v[72:75]
	v_mfma_f32_16x16x32_bf16 v[32:35], v[220:223], v[196:199], v[32:35]

; #define MFMA16(a, b, c) __builtin_amdgcn_mfma_f32_16x16x32_bf16(a, b, c, 0, 0, 0)
; template <int DH, int MODE>
; __device__ void attn_item(const Params& p, int layer, int b, int blk, int head, char* smem) {
;     ...
;     if (!wskip) {
;     if (MODE == 0) {
; #pragma unroll
;       for (int m = 0; m < 2; ++m)
; #pragma unroll
;         for (int j = 0; j < 4; ++j) {
;           float al = alpha_s[wid * 32 + m * 16 + fq * 4 + j];
; #pragma unroll
;           for (int n = 0; n < NDT; ++n) o[m][n][j] *= al;
;         }
;     }
; #pragma unroll
;     for (int ks = 0; ks < 2; ++ks) {
;       bf16x8 af[2];
; #pragma unroll
;       for (int m = 0; m < 2; ++m)
;         af[m] = *reinterpret_cast<const bf16x8*>(Pb + ks * 8192 + (wid * 32 + m * 16 + fr) * 64 + fq * 16);
; #pragma unroll
;       for (int n = 0; n < NDT; ++n) {
;         bf16x8 bfr = *reinterpret_cast<const bf16x8*>(smem + ks * (DH * 64) + (n * 16 + fr) * 64 + fq * 16);
; #pragma unroll
;         for (int m = 0; m < 2; ++m) o[m][n] = MFMA16(af[m], bfr, o[m][n]);
;       }
;     }
.LBB0_509:
	s_or_b64 exec, exec, s[54:55]
	s_waitcnt lgkmcnt(0)
	s_barrier
	s_and_saveexec_b64 s[14:15], s[52:53]
	s_cbranch_execz .LBB0_484
	ds_read_b128 v[164:167], v99 offset:51200
	ds_read_b128 v[168:171], v98 offset:8192
	ds_read_b128 v[172:175], v99 offset:52224
	ds_read_b128 v[176:179], v100
	ds_read_b128 v[180:183], v98 offset:8256
	ds_read_b128 v[184:187], v100 offset:1024
	ds_read_b128 v[188:191], v100 offset:2048
	ds_read_b128 v[192:195], v100 offset:3072
	ds_read_b128 v[196:199], v99 offset:59392
	ds_read_b128 v[200:203], v99 offset:60416
	ds_read_b128 v[204:207], v100 offset:4096
	ds_read_b128 v[208:211], v100 offset:5120
	ds_read_b128 v[212:215], v100 offset:6144
	ds_read_b128 v[216:219], v100 offset:7168
	s_waitcnt lgkmcnt(12)
	v_pk_mul_f32 v[18:19], v[18:19], v[170:171]
	v_pk_mul_f32 v[16:17], v[16:17], v[168:169]
	v_pk_mul_f32 v[30:31], v[30:31], v[170:171]
	s_waitcnt lgkmcnt(9)
	v_pk_mul_f32 v[14:15], v[14:15], v[182:183]
	v_pk_mul_f32 v[12:13], v[12:13], v[180:181]
	v_pk_mul_f32 v[28:29], v[28:29], v[168:169]
	v_pk_mul_f32 v[10:11], v[10:11], v[182:183]
	v_pk_mul_f32 v[8:9], v[8:9], v[180:181]
	v_mfma_f32_16x16x32_bf16 v[16:19], v[164:167], v[176:179], v[16:19]
	v_mul_f32_e64 v26, v26, v170
	v_mul_f32_e64 v27, v27, v171
	v_pk_mul_f32 v[24:25], v[24:25], v[168:169]
	v_pk_mul_f32 v[22:23], v[22:23], v[170:171]
	v_mfma_f32_16x16x32_bf16 v[12:15], v[172:175], v[176:179], v[12:15]
	v_pk_mul_f32 v[20:21], v[20:21], v[168:169]
	v_pk_mul_f32 v[6:7], v[6:7], v[182:183]
	s_waitcnt lgkmcnt(8)
	v_mfma_f32_16x16x32_bf16 v[28:31], v[164:167], v[184:187], v[28:31]
	v_mul_f32_e64 v4, v4, v180
	v_mul_f32_e64 v5, v5, v181
	v_pk_mul_f32 v[2:3], v[2:3], v[182:183]
	v_pk_mul_f32 v[0:1], v[0:1], v[180:181]
	v_mfma_f32_16x16x32_bf16 v[8:11], v[172:175], v[184:187], v[8:11]
	s_waitcnt lgkmcnt(7)
	v_mfma_f32_16x16x32_bf16 v[24:27], v[164:167], v[188:191], v[24:27]
	s_waitcnt lgkmcnt(6)
	v_mfma_f32_16x16x32_bf16 v[20:23], v[164:167], v[192:195], v[20:23]
	v_mfma_f32_16x16x32_bf16 v[4:7], v[172:175], v[188:191], v[4:7]
	v_mfma_f32_16x16x32_bf16 v[0:3], v[172:175], v[192:195], v[0:3]
	s_waitcnt lgkmcnt(3)
	v_mfma_f32_16x16x32_bf16 v[16:19], v[196:199], v[204:207], v[16:19]
	v_mfma_f32_16x16x32_bf16 v[12:15], v[200:203], v[204:207], v[12:15]
	s_waitcnt lgkmcnt(2)
	v_mfma_f32_16x16x32_bf16 v[28:31], v[196:199], v[208:211], v[28:31]
	v_mfma_f32_16x16x32_bf16 v[8:11], v[200:203], v[208:211], v[8:11]
	s_waitcnt lgkmcnt(1)
	v_mfma_f32_16x16x32_bf16 v[24:27], v[196:199], v[212:215], v[24:27]
	v_mfma_f32_16x16x32_bf16 v[4:7], v[200:203], v[212:215], v[4:7]
	s_waitcnt lgkmcnt(0)
	v_mfma_f32_16x16x32_bf16 v[20:23], v[196:199], v[216:219], v[20:23]
	v_mfma_f32_16x16x32_bf16 v[0:3], v[200:203], v[216:219], v[0:3]
	s_branch .LBB0_484

; #define MFMA16(a, b, c) __builtin_amdgcn_mfma_f32_16x16x32_bf16(a, b, c, 0, 0, 0)
; template <int DH, int MODE>
; __device__ void attn_item(const Params& p, int layer, int b, int blk, int head, char* smem) {
;     ...
; #pragma unroll
;     for (int ks = 0; ks < 2; ++ks) {
;       bf16x8 af[2];
; #pragma unroll
;       for (int m = 0; m < 2; ++m)
;         af[m] = *reinterpret_cast<const bf16x8*>(Pb + ks * 8192 + (wid * 32 + m * 16 + fr) * 64 + fq * 16);
; #pragma unroll
;       for (int n = 0; n < NDT; ++n) {
;         bf16x8 bfr = *reinterpret_cast<const bf16x8*>(smem + ks * (DH * 64) + (n * 16 + fr) * 64 + fq * 16);
; #pragma unroll
;         for (int m = 0; m < 2; ++m) o[m][n] = MFMA16(af[m], bfr, o[m][n]);
;       }
;     }
.LBB0_535:
	s_or_b64 exec, exec, s[52:53]
	s_waitcnt lgkmcnt(0)
	s_barrier
	s_and_saveexec_b64 s[52:53], s[16:17]
	s_cbranch_execz .LBB0_537
	ds_read_b128 v[176:179], v172 offset:51200
	ds_read_b128 v[180:183], v172 offset:52224
	ds_read_b128 v[184:187], v128
	ds_read_b128 v[188:191], v128 offset:1024
	ds_read_b128 v[192:195], v128 offset:2048
	ds_read_b128 v[196:199], v128 offset:3072
	ds_read_b128 v[200:203], v128 offset:4096
	ds_read_b128 v[204:207], v128 offset:5120
	ds_read_b128 v[208:211], v128 offset:6144
	ds_read_b128 v[212:215], v128 offset:7168
	ds_read_b128 v[216:219], v172 offset:59392
	ds_read_b128 v[220:223], v172 offset:60416
	ds_read_b128 v[224:227], v128 offset:8192
	ds_read_b128 v[228:231], v128 offset:9216
	s_waitcnt lgkmcnt(11)
	v_mfma_f32_16x16x32_bf16 v[12:15], v[176:179], v[184:187], v[12:15]
	v_mfma_f32_16x16x32_bf16 v[16:19], v[180:183], v[184:187], v[16:19]
	s_waitcnt lgkmcnt(10)
	v_mfma_f32_16x16x32_bf16 v[48:51], v[176:179], v[188:191], v[48:51]
	v_mfma_f32_16x16x32_bf16 v[20:23], v[180:183], v[188:191], v[20:23]
	s_waitcnt lgkmcnt(9)
	v_mfma_f32_16x16x32_bf16 v[52:55], v[176:179], v[192:195], v[52:55]
	v_mfma_f32_16x16x32_bf16 v[24:27], v[180:183], v[192:195], v[24:27]
	s_waitcnt lgkmcnt(8)
	v_mfma_f32_16x16x32_bf16 v[56:59], v[176:179], v[196:199], v[56:59]
	v_mfma_f32_16x16x32_bf16 v[36:39], v[180:183], v[196:199], v[36:39]
	s_waitcnt lgkmcnt(7)
	v_mfma_f32_16x16x32_bf16 v[60:63], v[176:179], v[200:203], v[60:63]
	v_mfma_f32_16x16x32_bf16 v[28:31], v[180:183], v[200:203], v[28:31]
	s_waitcnt lgkmcnt(6)
	v_mfma_f32_16x16x32_bf16 v[64:67], v[176:179], v[204:207], v[64:67]
	v_mfma_f32_16x16x32_bf16 v[40:43], v[180:183], v[204:207], v[40:43]
	s_waitcnt lgkmcnt(5)
	v_mfma_f32_16x16x32_bf16 v[68:71], v[176:179], v[208:211], v[68:71]
	s_waitcnt lgkmcnt(4)
	v_mfma_f32_16x16x32_bf16 v[72:75], v[176:179], v[212:215], v[72:75]
	ds_read_b128 v[176:179], v128 offset:10240
	v_mfma_f32_16x16x32_bf16 v[44:47], v[180:183], v[208:211], v[44:47]
	v_mfma_f32_16x16x32_bf16 v[32:35], v[180:183], v[212:215], v[32:35]
	ds_read_b128 v[180:183], v128 offset:11264
	ds_read_b128 v[184:187], v128 offset:12288
	ds_read_b128 v[188:191], v128 offset:13312
	ds_read_b128 v[192:195], v128 offset:14336
	ds_read_b128 v[196:199], v128 offset:15360
	s_waitcnt lgkmcnt(7)
	v_mfma_f32_16x16x32_bf16 v[12:15], v[216:219], v[224:227], v[12:15]
	v_mfma_f32_16x16x32_bf16 v[16:19], v[220:223], v[224:227], v[16:19]
	s_waitcnt lgkmcnt(6)
	v_mfma_f32_16x16x32_bf16 v[48:51], v[216:219], v[228:231], v[48:51]
	v_mfma_f32_16x16x32_bf16 v[20:23], v[220:223], v[228:231], v[20:23]
	s_waitcnt lgkmcnt(5)
	v_mfma_f32_16x16x32_bf16 v[52:55], v[216:219], v[176:179], v[52:55]
	v_mfma_f32_16x16x32_bf16 v[24:27], v[220:223], v[176:179], v[24:27]
	s_waitcnt lgkmcnt(4)
	v_mfma_f32_16x16x32_bf16 v[56:59], v[216:219], v[180:183], v[56:59]
	v_mfma_f32_16x16x32_bf16 v[36:39], v[220:223], v[180:183], v[36:39]
	s_waitcnt lgkmcnt(3)
	v_mfma_f32_16x16x32_bf16 v[60:63], v[216:219], v[184:187], v[60:63]
	v_mfma_f32_16x16x32_bf16 v[28:31], v[220:223], v[184:187], v[28:31]
	s_waitcnt lgkmcnt(2)
	v_mfma_f32_16x16x32_bf16 v[64:67], v[216:219], v[188:191], v[64:67]
	v_mfma_f32_16x16x32_bf16 v[40:43], v[220:223], v[188:191], v[40:43]
	s_waitcnt lgkmcnt(1)
	v_mfma_f32_16x16x32_bf16 v[68:71], v[216:219], v[192:195], v[68:71]
	v_mfma_f32_16x16x32_bf16 v[44:47], v[220:223], v[192:195], v[44:47]
	s_waitcnt lgkmcnt(0)
	v_mfma_f32_16x16x32_bf16 v[72:75], v[216:219], v[196:199], v[72:75]
	v_mfma_f32_16x16x32_bf16 v[32:35], v[220:223], v[196:199], v[32:35]

; #define MFMA16(a, b, c) __builtin_amdgcn_mfma_f32_16x16x32_bf16(a, b, c, 0, 0, 0)
; template <int DH, int MODE>
; __device__ void attn_item(const Params& p, int layer, int b, int blk, int head, char* smem) {
;     ...
;     if (!wskip) {
;     if (MODE == 0) {
; #pragma unroll
;       for (int m = 0; m < 2; ++m)
; #pragma unroll
;         for (int j = 0; j < 4; ++j) {
;           float al = alpha_s[wid * 32 + m * 16 + fq * 4 + j];
; #pragma unroll
;           for (int n = 0; n < NDT; ++n) o[m][n][j] *= al;
;         }
;     }
; #pragma unroll
;     for (int ks = 0; ks < 2; ++ks) {
;       bf16x8 af[2];
; #pragma unroll
;       for (int m = 0; m < 2; ++m)
;         af[m] = *reinterpret_cast<const bf16x8*>(Pb + ks * 8192 + (wid * 32 + m * 16 + fr) * 64 + fq * 16);
; #pragma unroll
;       for (int n = 0; n < NDT; ++n) {
;         bf16x8 bfr = *reinterpret_cast<const bf16x8*>(smem + ks * (DH * 64) + (n * 16 + fr) * 64 + fq * 16);
; #pragma unroll
;         for (int m = 0; m < 2; ++m) o[m][n] = MFMA16(af[m], bfr, o[m][n]);
;       }
;     }
.LBB0_830:
	s_or_b64 exec, exec, s[52:53]
	s_waitcnt lgkmcnt(0)
	s_barrier
	s_and_saveexec_b64 s[14:15], s[50:51]
	s_cbranch_execz .LBB0_805
	ds_read_b128 v[164:167], v99 offset:51200
	ds_read_b128 v[168:171], v98 offset:8192
	ds_read_b128 v[172:175], v99 offset:52224
	ds_read_b128 v[176:179], v100
	ds_read_b128 v[180:183], v98 offset:8256
	ds_read_b128 v[184:187], v100 offset:1024
	ds_read_b128 v[188:191], v100 offset:2048
	ds_read_b128 v[192:195], v100 offset:3072
	ds_read_b128 v[196:199], v99 offset:59392
	ds_read_b128 v[200:203], v99 offset:60416
	ds_read_b128 v[204:207], v100 offset:4096
	ds_read_b128 v[208:211], v100 offset:5120
	ds_read_b128 v[212:215], v100 offset:6144
	ds_read_b128 v[216:219], v100 offset:7168
	s_waitcnt lgkmcnt(12)
	v_pk_mul_f32 v[18:19], v[18:19], v[170:171]
	v_pk_mul_f32 v[16:17], v[16:17], v[168:169]
	v_pk_mul_f32 v[30:31], v[30:31], v[170:171]
	s_waitcnt lgkmcnt(9)
	v_pk_mul_f32 v[14:15], v[14:15], v[182:183]
	v_pk_mul_f32 v[12:13], v[12:13], v[180:181]
	v_pk_mul_f32 v[28:29], v[28:29], v[168:169]
	v_pk_mul_f32 v[10:11], v[10:11], v[182:183]
	v_pk_mul_f32 v[8:9], v[8:9], v[180:181]
	v_mfma_f32_16x16x32_bf16 v[16:19], v[164:167], v[176:179], v[16:19]
	v_mul_f32_e64 v26, v26, v170
	v_mul_f32_e64 v27, v27, v171
	v_pk_mul_f32 v[24:25], v[24:25], v[168:169]
	v_pk_mul_f32 v[22:23], v[22:23], v[170:171]
	v_mfma_f32_16x16x32_bf16 v[12:15], v[172:175], v[176:179], v[12:15]
	v_pk_mul_f32 v[20:21], v[20:21], v[168:169]
	v_pk_mul_f32 v[6:7], v[6:7], v[182:183]
	s_waitcnt lgkmcnt(8)
	v_mfma_f32_16x16x32_bf16 v[28:31], v[164:167], v[184:187], v[28:31]
	v_mul_f32_e64 v4, v4, v180
	v_mul_f32_e64 v5, v5, v181
	v_pk_mul_f32 v[2:3], v[2:3], v[182:183]
	v_pk_mul_f32 v[0:1], v[0:1], v[180:181]
	v_mfma_f32_16x16x32_bf16 v[8:11], v[172:175], v[184:187], v[8:11]
	s_waitcnt lgkmcnt(7)
	v_mfma_f32_16x16x32_bf16 v[24:27], v[164:167], v[188:191], v[24:27]
	s_waitcnt lgkmcnt(6)
	v_mfma_f32_16x16x32_bf16 v[20:23], v[164:167], v[192:195], v[20:23]
	v_mfma_f32_16x16x32_bf16 v[4:7], v[172:175], v[188:191], v[4:7]
	v_mfma_f32_16x16x32_bf16 v[0:3], v[172:175], v[192:195], v[0:3]
	s_waitcnt lgkmcnt(3)
	v_mfma_f32_16x16x32_bf16 v[16:19], v[196:199], v[204:207], v[16:19]
	v_mfma_f32_16x16x32_bf16 v[12:15], v[200:203], v[204:207], v[12:15]
	s_waitcnt lgkmcnt(2)
	v_mfma_f32_16x16x32_bf16 v[28:31], v[196:199], v[208:211], v[28:31]
	v_mfma_f32_16x16x32_bf16 v[8:11], v[200:203], v[208:211], v[8:11]
	s_waitcnt lgkmcnt(1)
	v_mfma_f32_16x16x32_bf16 v[24:27], v[196:199], v[212:215], v[24:27]
	v_mfma_f32_16x16x32_bf16 v[4:7], v[200:203], v[212:215], v[4:7]
	s_waitcnt lgkmcnt(0)
	v_mfma_f32_16x16x32_bf16 v[20:23], v[196:199], v[216:219], v[20:23]
	v_mfma_f32_16x16x32_bf16 v[0:3], v[200:203], v[216:219], v[0:3]
	s_branch .LBB0_805

; #define MFMA16(a, b, c) __builtin_amdgcn_mfma_f32_16x16x32_bf16(a, b, c, 0, 0, 0)
; template <int DH, int MODE>
; __device__ void attn_item(const Params& p, int layer, int b, int blk, int head, char* smem) {
;     ...
; #pragma unroll
;     for (int ks = 0; ks < 2; ++ks) {
;       bf16x8 af[2];
; #pragma unroll
;       for (int m = 0; m < 2; ++m)
;         af[m] = *reinterpret_cast<const bf16x8*>(Pb + ks * 8192 + (wid * 32 + m * 16 + fr) * 64 + fq * 16);
; #pragma unroll
;       for (int n = 0; n < NDT; ++n) {
;         bf16x8 bfr = *reinterpret_cast<const bf16x8*>(smem + ks * (DH * 64) + (n * 16 + fr) * 64 + fq * 16);
; #pragma unroll
;         for (int m = 0; m < 2; ++m) o[m][n] = MFMA16(af[m], bfr, o[m][n]);
;       }
;     }
.LBB0_856:
	s_or_b64 exec, exec, s[50:51]
	s_waitcnt lgkmcnt(0)
	s_barrier
	s_and_saveexec_b64 s[50:51], s[16:17]
	s_cbranch_execz .LBB0_858
	ds_read_b128 v[176:179], v172 offset:51200
	ds_read_b128 v[180:183], v172 offset:52224
	ds_read_b128 v[184:187], v128
	ds_read_b128 v[188:191], v128 offset:1024
	ds_read_b128 v[192:195], v128 offset:2048
	ds_read_b128 v[196:199], v128 offset:3072
	ds_read_b128 v[200:203], v128 offset:4096
	ds_read_b128 v[204:207], v128 offset:5120
	ds_read_b128 v[208:211], v128 offset:6144
	ds_read_b128 v[212:215], v128 offset:7168
	ds_read_b128 v[216:219], v172 offset:59392
	ds_read_b128 v[220:223], v172 offset:60416
	ds_read_b128 v[224:227], v128 offset:8192
	ds_read_b128 v[228:231], v128 offset:9216
	s_waitcnt lgkmcnt(11)
	v_mfma_f32_16x16x32_bf16 v[12:15], v[176:179], v[184:187], v[12:15]
	v_mfma_f32_16x16x32_bf16 v[16:19], v[180:183], v[184:187], v[16:19]
	s_waitcnt lgkmcnt(10)
	v_mfma_f32_16x16x32_bf16 v[48:51], v[176:179], v[188:191], v[48:51]
	v_mfma_f32_16x16x32_bf16 v[20:23], v[180:183], v[188:191], v[20:23]
	s_waitcnt lgkmcnt(9)
	v_mfma_f32_16x16x32_bf16 v[52:55], v[176:179], v[192:195], v[52:55]
	v_mfma_f32_16x16x32_bf16 v[24:27], v[180:183], v[192:195], v[24:27]
	s_waitcnt lgkmcnt(8)
	v_mfma_f32_16x16x32_bf16 v[56:59], v[176:179], v[196:199], v[56:59]
	v_mfma_f32_16x16x32_bf16 v[36:39], v[180:183], v[196:199], v[36:39]
	s_waitcnt lgkmcnt(7)
	v_mfma_f32_16x16x32_bf16 v[60:63], v[176:179], v[200:203], v[60:63]
	v_mfma_f32_16x16x32_bf16 v[28:31], v[180:183], v[200:203], v[28:31]
	s_waitcnt lgkmcnt(6)
	v_mfma_f32_16x16x32_bf16 v[64:67], v[176:179], v[204:207], v[64:67]
	v_mfma_f32_16x16x32_bf16 v[40:43], v[180:183], v[204:207], v[40:43]
	s_waitcnt lgkmcnt(5)
	v_mfma_f32_16x16x32_bf16 v[68:71], v[176:179], v[208:211], v[68:71]
	s_waitcnt lgkmcnt(4)
	v_mfma_f32_16x16x32_bf16 v[72:75], v[176:179], v[212:215], v[72:75]
	ds_read_b128 v[176:179], v128 offset:10240
	v_mfma_f32_16x16x32_bf16 v[44:47], v[180:183], v[208:211], v[44:47]
	v_mfma_f32_16x16x32_bf16 v[32:35], v[180:183], v[212:215], v[32:35]
	ds_read_b128 v[180:183], v128 offset:11264
	ds_read_b128 v[184:187], v128 offset:12288
	ds_read_b128 v[188:191], v128 offset:13312
	ds_read_b128 v[192:195], v128 offset:14336
	ds_read_b128 v[196:199], v128 offset:15360
	s_waitcnt lgkmcnt(7)
	v_mfma_f32_16x16x32_bf16 v[12:15], v[216:219], v[224:227], v[12:15]
	v_mfma_f32_16x16x32_bf16 v[16:19], v[220:223], v[224:227], v[16:19]
	s_waitcnt lgkmcnt(6)
	v_mfma_f32_16x16x32_bf16 v[48:51], v[216:219], v[228:231], v[48:51]
	v_mfma_f32_16x16x32_bf16 v[20:23], v[220:223], v[228:231], v[20:23]
	s_waitcnt lgkmcnt(5)
	v_mfma_f32_16x16x32_bf16 v[52:55], v[216:219], v[176:179], v[52:55]
	v_mfma_f32_16x16x32_bf16 v[24:27], v[220:223], v[176:179], v[24:27]
	s_waitcnt lgkmcnt(4)
	v_mfma_f32_16x16x32_bf16 v[56:59], v[216:219], v[180:183], v[56:59]
	v_mfma_f32_16x16x32_bf16 v[36:39], v[220:223], v[180:183], v[36:39]
	s_waitcnt lgkmcnt(3)
	v_mfma_f32_16x16x32_bf16 v[60:63], v[216:219], v[184:187], v[60:63]
	v_mfma_f32_16x16x32_bf16 v[28:31], v[220:223], v[184:187], v[28:31]
	s_waitcnt lgkmcnt(2)
	v_mfma_f32_16x16x32_bf16 v[64:67], v[216:219], v[188:191], v[64:67]
	v_mfma_f32_16x16x32_bf16 v[40:43], v[220:223], v[188:191], v[40:43]
	s_waitcnt lgkmcnt(1)
	v_mfma_f32_16x16x32_bf16 v[68:71], v[216:219], v[192:195], v[68:71]
	v_mfma_f32_16x16x32_bf16 v[44:47], v[220:223], v[192:195], v[44:47]
	s_waitcnt lgkmcnt(0)
	v_mfma_f32_16x16x32_bf16 v[72:75], v[216:219], v[196:199], v[72:75]
	v_mfma_f32_16x16x32_bf16 v[32:35], v[220:223], v[196:199], v[32:35]

; #define MFMA16(a, b, c) __builtin_amdgcn_mfma_f32_16x16x32_bf16(a, b, c, 0, 0, 0)
; template <int DH, int MODE>
; __device__ void attn_item(const Params& p, int layer, int b, int blk, int head, char* smem) {
;     ...
;     if (!wskip) {
;     if (MODE == 0) {
; #pragma unroll
;       for (int m = 0; m < 2; ++m)
; #pragma unroll
;         for (int j = 0; j < 4; ++j) {
;           float al = alpha_s[wid * 32 + m * 16 + fq * 4 + j];
; #pragma unroll
;           for (int n = 0; n < NDT; ++n) o[m][n][j] *= al;
;         }
;     }
; #pragma unroll
;     for (int ks = 0; ks < 2; ++ks) {
;       bf16x8 af[2];
; #pragma unroll
;       for (int m = 0; m < 2; ++m)
;         af[m] = *reinterpret_cast<const bf16x8*>(Pb + ks * 8192 + (wid * 32 + m * 16 + fr) * 64 + fq * 16);
; #pragma unroll
;       for (int n = 0; n < NDT; ++n) {
;         bf16x8 bfr = *reinterpret_cast<const bf16x8*>(smem + ks * (DH * 64) + (n * 16 + fr) * 64 + fq * 16);
; #pragma unroll
;         for (int m = 0; m < 2; ++m) o[m][n] = MFMA16(af[m], bfr, o[m][n]);
;       }
;     }
.LBB0_1151:
	s_or_b64 exec, exec, s[46:47]
	s_waitcnt lgkmcnt(0)
	s_barrier
	s_and_saveexec_b64 s[8:9], s[44:45]
	s_cbranch_execz .LBB0_1126
	ds_read_b128 v[164:167], v99 offset:51200
	ds_read_b128 v[168:171], v98 offset:8192
	ds_read_b128 v[172:175], v99 offset:52224
	ds_read_b128 v[176:179], v100
	ds_read_b128 v[180:183], v98 offset:8256
	ds_read_b128 v[184:187], v100 offset:1024
	ds_read_b128 v[188:191], v100 offset:2048
	ds_read_b128 v[192:195], v100 offset:3072
	ds_read_b128 v[196:199], v99 offset:59392
	ds_read_b128 v[200:203], v99 offset:60416
	ds_read_b128 v[204:207], v100 offset:4096
	ds_read_b128 v[208:211], v100 offset:5120
	ds_read_b128 v[212:215], v100 offset:6144
	ds_read_b128 v[216:219], v100 offset:7168
	s_waitcnt lgkmcnt(12)
	v_pk_mul_f32 v[18:19], v[18:19], v[170:171]
	v_pk_mul_f32 v[16:17], v[16:17], v[168:169]
	v_pk_mul_f32 v[30:31], v[30:31], v[170:171]
	s_waitcnt lgkmcnt(9)
	v_pk_mul_f32 v[14:15], v[14:15], v[182:183]
	v_pk_mul_f32 v[12:13], v[12:13], v[180:181]
	v_pk_mul_f32 v[28:29], v[28:29], v[168:169]
	v_pk_mul_f32 v[10:11], v[10:11], v[182:183]
	v_pk_mul_f32 v[8:9], v[8:9], v[180:181]
	v_mfma_f32_16x16x32_bf16 v[16:19], v[164:167], v[176:179], v[16:19]
	v_mul_f32_e64 v26, v26, v170
	v_mul_f32_e64 v27, v27, v171
	v_pk_mul_f32 v[24:25], v[24:25], v[168:169]
	v_pk_mul_f32 v[22:23], v[22:23], v[170:171]
	v_mfma_f32_16x16x32_bf16 v[12:15], v[172:175], v[176:179], v[12:15]
	v_pk_mul_f32 v[20:21], v[20:21], v[168:169]
	v_pk_mul_f32 v[6:7], v[6:7], v[182:183]
	s_waitcnt lgkmcnt(8)
	v_mfma_f32_16x16x32_bf16 v[28:31], v[164:167], v[184:187], v[28:31]
	v_mul_f32_e64 v4, v4, v180
	v_mul_f32_e64 v5, v5, v181
	v_pk_mul_f32 v[2:3], v[2:3], v[182:183]
	v_pk_mul_f32 v[0:1], v[0:1], v[180:181]
	v_mfma_f32_16x16x32_bf16 v[8:11], v[172:175], v[184:187], v[8:11]
	s_waitcnt lgkmcnt(7)
	v_mfma_f32_16x16x32_bf16 v[24:27], v[164:167], v[188:191], v[24:27]
	s_waitcnt lgkmcnt(6)
	v_mfma_f32_16x16x32_bf16 v[20:23], v[164:167], v[192:195], v[20:23]
	v_mfma_f32_16x16x32_bf16 v[4:7], v[172:175], v[188:191], v[4:7]
	v_mfma_f32_16x16x32_bf16 v[0:3], v[172:175], v[192:195], v[0:3]
	s_waitcnt lgkmcnt(3)
	v_mfma_f32_16x16x32_bf16 v[16:19], v[196:199], v[204:207], v[16:19]
	v_mfma_f32_16x16x32_bf16 v[12:15], v[200:203], v[204:207], v[12:15]
	s_waitcnt lgkmcnt(2)
	v_mfma_f32_16x16x32_bf16 v[28:31], v[196:199], v[208:211], v[28:31]
	v_mfma_f32_16x16x32_bf16 v[8:11], v[200:203], v[208:211], v[8:11]
	s_waitcnt lgkmcnt(1)
	v_mfma_f32_16x16x32_bf16 v[24:27], v[196:199], v[212:215], v[24:27]
	v_mfma_f32_16x16x32_bf16 v[4:7], v[200:203], v[212:215], v[4:7]
	s_waitcnt lgkmcnt(0)
	v_mfma_f32_16x16x32_bf16 v[20:23], v[196:199], v[216:219], v[20:23]
	v_mfma_f32_16x16x32_bf16 v[0:3], v[200:203], v[216:219], v[0:3]
	s_branch .LBB0_1126

; #define MFMA16(a, b, c) __builtin_amdgcn_mfma_f32_16x16x32_bf16(a, b, c, 0, 0, 0)
; template <int DH, int MODE>
; __device__ void attn_item(const Params& p, int layer, int b, int blk, int head, char* smem) {
;     ...
; #pragma unroll
;     for (int ks = 0; ks < 2; ++ks) {
;       bf16x8 af[2];
; #pragma unroll
;       for (int m = 0; m < 2; ++m)
;         af[m] = *reinterpret_cast<const bf16x8*>(Pb + ks * 8192 + (wid * 32 + m * 16 + fr) * 64 + fq * 16);
; #pragma unroll
;       for (int n = 0; n < NDT; ++n) {
;         bf16x8 bfr = *reinterpret_cast<const bf16x8*>(smem + ks * (DH * 64) + (n * 16 + fr) * 64 + fq * 16);
; #pragma unroll
;         for (int m = 0; m < 2; ++m) o[m][n] = MFMA16(af[m], bfr, o[m][n]);
;       }
;     }
.LBB0_1177:
	s_or_b64 exec, exec, s[44:45]
	s_waitcnt lgkmcnt(0)
	s_barrier
	s_and_saveexec_b64 s[44:45], s[10:11]
	s_cbranch_execz .LBB0_1179
	ds_read_b128 v[176:179], v172 offset:51200
	ds_read_b128 v[180:183], v172 offset:52224
	ds_read_b128 v[184:187], v128
	ds_read_b128 v[188:191], v128 offset:1024
	ds_read_b128 v[192:195], v128 offset:2048
	ds_read_b128 v[196:199], v128 offset:3072
	ds_read_b128 v[200:203], v128 offset:4096
	ds_read_b128 v[204:207], v128 offset:5120
	ds_read_b128 v[208:211], v128 offset:6144
	ds_read_b128 v[212:215], v128 offset:7168
	ds_read_b128 v[216:219], v172 offset:59392
	ds_read_b128 v[220:223], v172 offset:60416
	ds_read_b128 v[224:227], v128 offset:8192
	ds_read_b128 v[228:231], v128 offset:9216
	s_waitcnt lgkmcnt(11)
	v_mfma_f32_16x16x32_bf16 v[12:15], v[176:179], v[184:187], v[12:15]
	v_mfma_f32_16x16x32_bf16 v[16:19], v[180:183], v[184:187], v[16:19]
	s_waitcnt lgkmcnt(10)
	v_mfma_f32_16x16x32_bf16 v[48:51], v[176:179], v[188:191], v[48:51]
	v_mfma_f32_16x16x32_bf16 v[20:23], v[180:183], v[188:191], v[20:23]
	s_waitcnt lgkmcnt(9)
	v_mfma_f32_16x16x32_bf16 v[52:55], v[176:179], v[192:195], v[52:55]
	v_mfma_f32_16x16x32_bf16 v[24:27], v[180:183], v[192:195], v[24:27]
	s_waitcnt lgkmcnt(8)
	v_mfma_f32_16x16x32_bf16 v[56:59], v[176:179], v[196:199], v[56:59]
	v_mfma_f32_16x16x32_bf16 v[36:39], v[180:183], v[196:199], v[36:39]
	s_waitcnt lgkmcnt(7)
	v_mfma_f32_16x16x32_bf16 v[60:63], v[176:179], v[200:203], v[60:63]
	v_mfma_f32_16x16x32_bf16 v[28:31], v[180:183], v[200:203], v[28:31]
	s_waitcnt lgkmcnt(6)
	v_mfma_f32_16x16x32_bf16 v[64:67], v[176:179], v[204:207], v[64:67]
	v_mfma_f32_16x16x32_bf16 v[40:43], v[180:183], v[204:207], v[40:43]
	s_waitcnt lgkmcnt(5)
	v_mfma_f32_16x16x32_bf16 v[68:71], v[176:179], v[208:211], v[68:71]
	s_waitcnt lgkmcnt(4)
	v_mfma_f32_16x16x32_bf16 v[72:75], v[176:179], v[212:215], v[72:75]
	ds_read_b128 v[176:179], v128 offset:10240
	v_mfma_f32_16x16x32_bf16 v[44:47], v[180:183], v[208:211], v[44:47]
	v_mfma_f32_16x16x32_bf16 v[32:35], v[180:183], v[212:215], v[32:35]
	ds_read_b128 v[180:183], v128 offset:11264
	ds_read_b128 v[184:187], v128 offset:12288
	ds_read_b128 v[188:191], v128 offset:13312
	ds_read_b128 v[192:195], v128 offset:14336
	ds_read_b128 v[196:199], v128 offset:15360
	s_waitcnt lgkmcnt(7)
	v_mfma_f32_16x16x32_bf16 v[12:15], v[216:219], v[224:227], v[12:15]
	v_mfma_f32_16x16x32_bf16 v[16:19], v[220:223], v[224:227], v[16:19]
	s_waitcnt lgkmcnt(6)
	v_mfma_f32_16x16x32_bf16 v[48:51], v[216:219], v[228:231], v[48:51]
	v_mfma_f32_16x16x32_bf16 v[20:23], v[220:223], v[228:231], v[20:23]
	s_waitcnt lgkmcnt(5)
	v_mfma_f32_16x16x32_bf16 v[52:55], v[216:219], v[176:179], v[52:55]
	v_mfma_f32_16x16x32_bf16 v[24:27], v[220:223], v[176:179], v[24:27]
	s_waitcnt lgkmcnt(4)
	v_mfma_f32_16x16x32_bf16 v[56:59], v[216:219], v[180:183], v[56:59]
	v_mfma_f32_16x16x32_bf16 v[36:39], v[220:223], v[180:183], v[36:39]
	s_waitcnt lgkmcnt(3)
	v_mfma_f32_16x16x32_bf16 v[60:63], v[216:219], v[184:187], v[60:63]
	v_mfma_f32_16x16x32_bf16 v[28:31], v[220:223], v[184:187], v[28:31]
	s_waitcnt lgkmcnt(2)
	v_mfma_f32_16x16x32_bf16 v[64:67], v[216:219], v[188:191], v[64:67]
	v_mfma_f32_16x16x32_bf16 v[40:43], v[220:223], v[188:191], v[40:43]
	s_waitcnt lgkmcnt(1)
	v_mfma_f32_16x16x32_bf16 v[68:71], v[216:219], v[192:195], v[68:71]
	v_mfma_f32_16x16x32_bf16 v[44:47], v[220:223], v[192:195], v[44:47]
	s_waitcnt lgkmcnt(0)
	v_mfma_f32_16x16x32_bf16 v[72:75], v[216:219], v[196:199], v[72:75]
	v_mfma_f32_16x16x32_bf16 v[32:35], v[220:223], v[196:199], v[32:35]
